# seams 7 and 11 made XCD-local (leader skips L2 write-back and cross-XCD level when the XCD-aware numbering is in force)
# speedup vs baseline: 1.0584x; 1.0125x over previous
.LBB0_382:
	s_andn2_b64 vcc, exec, s[0:1]
	v_mov_b32_e32 v1, s89
	s_cbranch_vccnz .LBB0_384
	v_readlane_b32 s1, v244, 12
	s_mul_i32 s0, s1, s24
	v_add_u32_e32 v1, s0, v0
	s_add_i32 s0, 0, 0x23fd4
	v_mov_b32_e32 v2, s0
	v_lshlrev_b32_e32 v0, 3, v0
	ds_write_b32 v2, v1
	v_mov_b32_e32 v3, 0x23fdc
	v_mov_b32_e32 v4, 1
	ds_write_b32 v3, v4
	v_or_b32_e32 v1, s1, v0

.LBB0_1837:
	s_andn2_saveexec_b64 s[8:9], s[8:9]
	s_cbranch_execz .LBB0_1857
	s_mov_b64 s[8:9], exec
	v_mov_b32_e32 v1, 0x23fdc
	ds_read_b32 v1, v1
	s_waitcnt lgkmcnt(0)
	s_nop 0
	v_readfirstlane_b32 s98, v1
	s_nop 3
	s_cmp_lg_u32 s98, 0
	s_cbranch_scc1 .LBB0_1854
	buffer_wbl2 sc1
	s_waitcnt lgkmcnt(0)
	s_waitcnt vmcnt(0)
	v_mbcnt_lo_u32_b32 v1, s8, 0
	v_mbcnt_hi_u32_b32 v1, s9, v1
	v_cmp_eq_u32_e32 vcc, 0, v1
	s_and_saveexec_b64 s[10:11], vcc
	s_cbranch_execz .LBB0_1840
	s_bcnt1_i32_b64 s8, s[8:9]
	v_readlane_b32 s12, v244, 0
	v_mov_b32_e32 v2, 0x1fd03000
	v_mov_b32_e32 v3, s8
	v_readlane_b32 s18, v244, 6
	v_readlane_b32 s19, v244, 7
	v_readlane_b32 s13, v244, 1
	v_readlane_b32 s14, v244, 2
	v_readlane_b32 s15, v244, 3
	v_readlane_b32 s16, v244, 4
	v_readlane_b32 s17, v244, 5
	global_atomic_add v2, v2, v3, s[18:19] offset:1024 sc0

.LBB0_2149:
	s_andn2_saveexec_b64 s[6:7], s[6:7]
	s_cbranch_execz .LBB0_2169
	s_mov_b64 s[6:7], exec
	v_mov_b32_e32 v1, 0x23fdc
	ds_read_b32 v1, v1
	s_waitcnt lgkmcnt(0)
	s_nop 0
	v_readfirstlane_b32 s98, v1
	s_nop 3
	s_cmp_lg_u32 s98, 0
	s_cbranch_scc1 .LBB0_2166
	buffer_wbl2 sc1
	s_waitcnt lgkmcnt(0)
	s_waitcnt vmcnt(0)
	v_mbcnt_lo_u32_b32 v1, s6, 0
	v_mbcnt_hi_u32_b32 v1, s7, v1
	v_cmp_eq_u32_e32 vcc, 0, v1
	s_and_saveexec_b64 s[8:9], vcc
	s_cbranch_execz .LBB0_2152
	s_bcnt1_i32_b64 s6, s[6:7]
	v_readlane_b32 s12, v244, 0
	v_mov_b32_e32 v2, 0x1fd03000
	v_mov_b32_e32 v3, s6
	v_readlane_b32 s18, v244, 6
	v_readlane_b32 s19, v244, 7
	v_readlane_b32 s13, v244, 1
	v_readlane_b32 s14, v244, 2
	v_readlane_b32 s15, v244, 3
	v_readlane_b32 s16, v244, 4
	v_readlane_b32 s17, v244, 5
	global_atomic_add v2, v2, v3, s[18:19] offset:1024 sc0
